# grid barrier: acquire-side cache invalidate issued at arrival (completes under the wait), every block still invalidates once per barrier
# speedup vs baseline: 1.0169x; 1.0169x over previous
; __device__ __forceinline__ unsigned xb_ld(unsigned* p) { return __hip_atomic_load(p, __ATOMIC_RELAXED, __HIP_MEMORY_SCOPE_AGENT); }
; __device__ __forceinline__ unsigned xb_add(unsigned* p, unsigned v) { return __hip_atomic_fetch_add(p, v, __ATOMIC_RELAXED, __HIP_MEMORY_SCOPE_AGENT); }
; #define XB_SPIN(cond, bar) do { unsigned _sp = 0; while (cond) { __builtin_amdgcn_s_sleep(1); \
;     if ((++_sp & 255u) == 0u) { if (xb_ld(&(bar)[XB_TMO])) break; if (_sp > XB_SPIN_CAP) { atomicAdd(&(bar)[XB_TMO], 1u); break; } } } } while (0)
; __device__ __forceinline__ void xcd_barrier(const XcdBarrier& b) {
;   asm volatile("s_waitcnt vmcnt(0)" ::: "memory");
;   __syncthreads();
;   if (threadIdx.x == 0) {
;     unsigned* bar = b.bar;
;     __builtin_amdgcn_s_waitcnt(0);
;     unsigned nloc = b.st[0], nx = b.st[1];
;     if (nloc == 0u) { xcd_barrier_complete(bar, b.x, nloc, nx); b.st[0] = nloc; b.st[1] = nx; }
;     const unsigned old = xb_add(&bar[XB_XSUB(b.x)], 1u);
;     const unsigned gen = old / nloc;
;     if (old + 1u == (gen + 1u) * nloc) {
;       __builtin_amdgcn_fence(__ATOMIC_RELEASE, "agent");
;       asm volatile("s_waitcnt vmcnt(0)" ::: "memory");
;       const unsigned og = xb_add(&bar[XB_TOP], 1u);
;       const unsigned tg = og / nx;
;       if (og + 1u == (tg + 1u) * nx) xb_add(&bar[XB_TOPGEN], 1u);
;       else XB_SPIN(xb_ld(&bar[XB_TOPGEN]) == tg, bar);
;       __builtin_amdgcn_fence(__ATOMIC_ACQUIRE, "agent");
;       xb_add(&bar[XB_XGEN(b.x)], 1u);
;       asm volatile("s_waitcnt vmcnt(0)" ::: "memory");
;     } else {
;       XB_SPIN(xb_ld(&bar[XB_XGEN(b.x)]) == gen, bar);
;       __builtin_amdgcn_fence(__ATOMIC_ACQUIRE, "agent");
;       asm volatile("s_waitcnt vmcnt(0)" ::: "memory");
;     }
;   }
;   __syncthreads();
; }
.LBB0_75:
	s_waitcnt lgkmcnt(0)
	v_readlane_b32 s40, v242, 58
	v_readlane_b32 s41, v242, 59
	v_mov_b32_e32 v4, 1
	v_readlane_b32 s44, v240, 48
	s_add_i32 s44, s44, 1
	v_mul_lo_u32 v6, v3, s44
	v_mul_lo_u32 v5, v2, s44
	s_nop 1
	global_atomic_add v4, v1, v4, s[40:41] sc0
	buffer_inv sc1
	v_readlane_b32 s42, v242, 62
	v_readlane_b32 s43, v242, 63
	s_waitcnt vmcnt(1)
	v_add_u32_e32 v4, 1, v4
	v_cmp_eq_u32_e32 vcc, v4, v6
	s_cbranch_vccz .Lgb0_poll
	buffer_wbl2 sc1
	s_waitcnt vmcnt(0) lgkmcnt(0)
	v_mov_b32_e32 v4, 1
	global_atomic_add v1, v4, s[42:43]

; __device__ __forceinline__ unsigned xb_ld(unsigned* p) { return __hip_atomic_load(p, __ATOMIC_RELAXED, __HIP_MEMORY_SCOPE_AGENT); }
; __device__ __forceinline__ unsigned xb_add(unsigned* p, unsigned v) { return __hip_atomic_fetch_add(p, v, __ATOMIC_RELAXED, __HIP_MEMORY_SCOPE_AGENT); }
; #define XB_SPIN(cond, bar) do { unsigned _sp = 0; while (cond) { __builtin_amdgcn_s_sleep(1); \
;     if ((++_sp & 255u) == 0u) { if (xb_ld(&(bar)[XB_TMO])) break; if (_sp > XB_SPIN_CAP) { atomicAdd(&(bar)[XB_TMO], 1u); break; } } } } while (0)
; #define GSYNC() xcd_barrier(xb)
; __device__ __forceinline__ void xcd_barrier(const XcdBarrier& b) {
;   asm volatile("s_waitcnt vmcnt(0)" ::: "memory");
;   __syncthreads();
;   if (threadIdx.x == 0) {
;     unsigned* bar = b.bar;
;     __builtin_amdgcn_s_waitcnt(0);
;     unsigned nloc = b.st[0], nx = b.st[1];
;     if (nloc == 0u) { xcd_barrier_complete(bar, b.x, nloc, nx); b.st[0] = nloc; b.st[1] = nx; }
;     const unsigned old = xb_add(&bar[XB_XSUB(b.x)], 1u);
;     const unsigned gen = old / nloc;
;     if (old + 1u == (gen + 1u) * nloc) {
;       __builtin_amdgcn_fence(__ATOMIC_RELEASE, "agent");
;       asm volatile("s_waitcnt vmcnt(0)" ::: "memory");
;       const unsigned og = xb_add(&bar[XB_TOP], 1u);
;       const unsigned tg = og / nx;
;       if (og + 1u == (tg + 1u) * nx) xb_add(&bar[XB_TOPGEN], 1u);
;       else XB_SPIN(xb_ld(&bar[XB_TOPGEN]) == tg, bar);
;       __builtin_amdgcn_fence(__ATOMIC_ACQUIRE, "agent");
;       xb_add(&bar[XB_XGEN(b.x)], 1u);
;       asm volatile("s_waitcnt vmcnt(0)" ::: "memory");
;     } else {
;       XB_SPIN(xb_ld(&bar[XB_XGEN(b.x)]) == gen, bar);
;       __builtin_amdgcn_fence(__ATOMIC_ACQUIRE, "agent");
;       asm volatile("s_waitcnt vmcnt(0)" ::: "memory");
;     }
;   }
;   __syncthreads();
; }
; __global__ void __launch_bounds__(256, 2) k_mega(Params p) {
;     ...
;   for (int l = 0; l < 2; ++l) {
;     ph_convert(p, l, smem);
;     GSYNC();
; #pragma unroll 1
;     for (int g = 0; g < NGRP; ++g) {
;       if (l == 0 && g == 0) { ph_prenorm(p, 0, 0); GSYNC(); }
;       if (g == 0) { ph_gemm_in_a(p, l, smem); GSYNC(); }
.Lgb0_done:
.LBB0_111:
	s_or_b64 exec, exec, s[38:39]
	v_readlane_b32 s98, v240, 48
	s_add_i32 s98, s98, 1
	s_nop 0
	v_writelane_b32 v240, s98, 48
	s_xor_b64 s[12:13], s[14:15], -1
	v_writelane_b32 v240, s12, 22
	v_readlane_b32 s10, v241, 59
	s_mul_i32 s92, s10, 0x6c00
	v_writelane_b32 v240, s13, 23
	s_lshl_b32 s12, s10, 10
	s_mov_b32 s13, s93
	v_writelane_b32 v240, s12, 24
	s_lshl_b64 s[38:39], s[12:13], 2
	s_mov_b64 s[44:45], s[14:15]
	v_writelane_b32 v240, s13, 25
	s_mov_b32 s59, 0x38e38e39
	v_readlane_b32 s12, v240, 4
	v_readlane_b32 s13, v240, 5
	s_add_u32 s12, s12, s38
	s_addc_u32 s13, s13, s39
	v_writelane_b32 v240, s12, 26
	s_lshl_b64 s[40:41], s[92:93], 2
	s_waitcnt lgkmcnt(0)
	v_writelane_b32 v240, s13, 27
	v_readlane_b32 s12, v241, 5
	v_readlane_b32 s13, v241, 6
	s_add_u32 s12, s12, s40
	s_addc_u32 s13, s13, s41
	v_writelane_b32 v240, s12, 28
	v_readlane_b32 s15, v241, 8
	s_mov_b32 s15, 0
	v_writelane_b32 v240, s13, 29
	s_lshl_b32 s12, s10, 3
	v_writelane_b32 v240, s12, 30
	s_lshl_b32 s12, s10, 4
	v_writelane_b32 v240, s12, 31
	s_lshl_b32 s12, s10, 8
	s_and_b64 s[40:41], s[44:45], exec
	v_writelane_b32 v240, s12, 32
	s_cselect_b32 s12, 16, 0xf8
	s_mov_b32 s13, s15
	v_writelane_b32 v240, s12, 33
	v_readlane_b32 s14, v241, 7
	v_readlane_b32 s40, v241, 9
	v_writelane_b32 v240, s13, 34
	s_mul_i32 s12, s10, 17
	s_mov_b32 s13, s93
	v_writelane_b32 v240, s12, 35
	s_cselect_b32 s14, 0, 0xa0
	v_readlane_b32 s41, v241, 10
	v_writelane_b32 v240, s13, 36
	s_add_u32 s12, s40, s38
	s_addc_u32 s13, s41, s39
	v_writelane_b32 v240, s12, 37
	s_barrier
	s_nop 0
	v_writelane_b32 v240, s13, 38
	v_readlane_b32 s12, v241, 60
	v_writelane_b32 v240, s44, 39
	s_and_b64 s[38:39], s[44:45], exec
	v_readlane_b32 s13, v241, 61
	v_writelane_b32 v240, s45, 40
	s_cselect_b32 s13, s13, s77
	s_cselect_b32 s12, s12, s76
	v_writelane_b32 v240, s12, 41
	v_readlane_b32 s42, v241, 11
	v_readlane_b32 s43, v241, 12
	v_writelane_b32 v240, s13, 42
	v_writelane_b32 v240, s14, 43
	s_mov_b32 s64, s15
	s_nop 0
	v_writelane_b32 v240, s15, 44
	s_movk_i32 s14, 0x3000
	s_branch .LBB0_114

; __device__ __forceinline__ unsigned xb_ld(unsigned* p) { return __hip_atomic_load(p, __ATOMIC_RELAXED, __HIP_MEMORY_SCOPE_AGENT); }
; __device__ __forceinline__ unsigned xb_add(unsigned* p, unsigned v) { return __hip_atomic_fetch_add(p, v, __ATOMIC_RELAXED, __HIP_MEMORY_SCOPE_AGENT); }
; #define XB_SPIN(cond, bar) do { unsigned _sp = 0; while (cond) { __builtin_amdgcn_s_sleep(1); \
;     if ((++_sp & 255u) == 0u) { if (xb_ld(&(bar)[XB_TMO])) break; if (_sp > XB_SPIN_CAP) { atomicAdd(&(bar)[XB_TMO], 1u); break; } } } } while (0)
; #define GSYNC() xcd_barrier(xb)
; __device__ __forceinline__ void xcd_barrier(const XcdBarrier& b) {
;   asm volatile("s_waitcnt vmcnt(0)" ::: "memory");
;   __syncthreads();
;   if (threadIdx.x == 0) {
;     unsigned* bar = b.bar;
;     __builtin_amdgcn_s_waitcnt(0);
;     unsigned nloc = b.st[0], nx = b.st[1];
;     if (nloc == 0u) { xcd_barrier_complete(bar, b.x, nloc, nx); b.st[0] = nloc; b.st[1] = nx; }
;     const unsigned old = xb_add(&bar[XB_XSUB(b.x)], 1u);
;     const unsigned gen = old / nloc;
;     if (old + 1u == (gen + 1u) * nloc) {
;       __builtin_amdgcn_fence(__ATOMIC_RELEASE, "agent");
;       asm volatile("s_waitcnt vmcnt(0)" ::: "memory");
;       const unsigned og = xb_add(&bar[XB_TOP], 1u);
;       const unsigned tg = og / nx;
;       if (og + 1u == (tg + 1u) * nx) xb_add(&bar[XB_TOPGEN], 1u);
;       else XB_SPIN(xb_ld(&bar[XB_TOPGEN]) == tg, bar);
;       __builtin_amdgcn_fence(__ATOMIC_ACQUIRE, "agent");
;       xb_add(&bar[XB_XGEN(b.x)], 1u);
;       asm volatile("s_waitcnt vmcnt(0)" ::: "memory");
;     } else {
;       XB_SPIN(xb_ld(&bar[XB_XGEN(b.x)]) == gen, bar);
;       __builtin_amdgcn_fence(__ATOMIC_ACQUIRE, "agent");
;       asm volatile("s_waitcnt vmcnt(0)" ::: "memory");
;     }
;   }
;   __syncthreads();
; }
; __global__ void __launch_bounds__(256, 2) k_mega(Params p) {
;     ...
;       if (l == 0 && g == 0) { ph_prenorm(p, 0, 0); GSYNC(); }
;       if (g == 0) { ph_gemm_in_a(p, l, smem); GSYNC(); }
.Lgb1_done:
.LBB0_175:
	s_or_b64 exec, exec, s[38:39]
	v_readlane_b32 s98, v240, 48
	s_add_i32 s98, s98, 1
	s_nop 0
	v_writelane_b32 v240, s98, 48
	v_readlane_b32 s64, v240, 45
	s_waitcnt lgkmcnt(0)
	s_barrier
	s_cmp_lg_u32 s64, 0
	s_cbranch_scc1 .LBB0_317

; __device__ __forceinline__ unsigned xb_ld(unsigned* p) { return __hip_atomic_load(p, __ATOMIC_RELAXED, __HIP_MEMORY_SCOPE_AGENT); }
; __device__ __forceinline__ unsigned xb_add(unsigned* p, unsigned v) { return __hip_atomic_fetch_add(p, v, __ATOMIC_RELAXED, __HIP_MEMORY_SCOPE_AGENT); }
; #define XB_SPIN(cond, bar) do { unsigned _sp = 0; while (cond) { __builtin_amdgcn_s_sleep(1); \
;     if ((++_sp & 255u) == 0u) { if (xb_ld(&(bar)[XB_TMO])) break; if (_sp > XB_SPIN_CAP) { atomicAdd(&(bar)[XB_TMO], 1u); break; } } } } while (0)
; #define GSYNC() xcd_barrier(xb)
; __device__ __forceinline__ void xcd_barrier(const XcdBarrier& b) {
;   asm volatile("s_waitcnt vmcnt(0)" ::: "memory");
;   __syncthreads();
;   if (threadIdx.x == 0) {
;     unsigned* bar = b.bar;
;     __builtin_amdgcn_s_waitcnt(0);
;     unsigned nloc = b.st[0], nx = b.st[1];
;     if (nloc == 0u) { xcd_barrier_complete(bar, b.x, nloc, nx); b.st[0] = nloc; b.st[1] = nx; }
;     const unsigned old = xb_add(&bar[XB_XSUB(b.x)], 1u);
;     const unsigned gen = old / nloc;
;     if (old + 1u == (gen + 1u) * nloc) {
;       __builtin_amdgcn_fence(__ATOMIC_RELEASE, "agent");
;       asm volatile("s_waitcnt vmcnt(0)" ::: "memory");
;       const unsigned og = xb_add(&bar[XB_TOP], 1u);
;       const unsigned tg = og / nx;
;       if (og + 1u == (tg + 1u) * nx) xb_add(&bar[XB_TOPGEN], 1u);
;       else XB_SPIN(xb_ld(&bar[XB_TOPGEN]) == tg, bar);
;       __builtin_amdgcn_fence(__ATOMIC_ACQUIRE, "agent");
;       xb_add(&bar[XB_XGEN(b.x)], 1u);
;       asm volatile("s_waitcnt vmcnt(0)" ::: "memory");
;     } else {
;       XB_SPIN(xb_ld(&bar[XB_XGEN(b.x)]) == gen, bar);
;       __builtin_amdgcn_fence(__ATOMIC_ACQUIRE, "agent");
;       asm volatile("s_waitcnt vmcnt(0)" ::: "memory");
;     }
;   }
;   __syncthreads();
; }
; __global__ void __launch_bounds__(256, 2) k_mega(Params p) {
;     ...
;       ph_conv(p, l); GSYNC();
.Lgb2_done:
.LBB0_316:
	s_or_b64 exec, exec, s[38:39]
	v_readlane_b32 s98, v240, 48
	s_add_i32 s98, s98, 1
	s_nop 0
	v_writelane_b32 v240, s98, 48
	s_waitcnt lgkmcnt(0)
	s_barrier

; __device__ void ph_gdn_prep(const Params& p, int l, char* smem) {
;   const int tid = otid();
;   const int lane = tid & 63, w = tid >> 6, fr = lane & 15, fq = lane >> 4;
;   PrepW& sw = ((PrepW*)smem)[w];
;   const int gw = blockIdx.x * 4 + w, nw = gridDim.x * 4;
;   for (int task = gw; task < 2304; task += nw) {
;     const int chunk = task % 72, r = task / 72, dir = r & 1, h = (r >> 1) & 3, bl = r >> 3;
;     const int tk = lane & 31;
;     const float* gp = p.gates + (long)scan_row(bl, dir, chunk * 32 + tk) * GLD;
;     float ig = gp[32 + dir * 4 + h] + p.ml_i_bias[l * 8 + dir * 4 + h];
;     float F = -softplusf_(-(gp[40 + dir * 4 + h] + p.ml_f_bias[l * 8 + dir * 4 + h]));
; #pragma unroll
;     for (int o = 1; o < 32; o <<= 1) { float t2 = __shfl_up(F, o); if (tk >= o) F += t2; }
;     float a = ig - F;
;     float pm = a;
; #pragma unroll
;     for (int o = 1; o < 32; o <<= 1) { float t2 = __shfl_up(pm, o); if (tk >= o) pm = fmaxf(pm, t2); }
;     if (lane < 32) { float* o_ = p.mprep + (long)task * 96; o_[tk] = F; o_[32 + tk] = a; o_[64 + tk] = pm; }
; __device__ __forceinline__ void xcd_barrier(const XcdBarrier& b) {
;   asm volatile("s_waitcnt vmcnt(0)" ::: "memory");
;   __syncthreads();
;   if (threadIdx.x == 0) {
;     unsigned* bar = b.bar;
;     __builtin_amdgcn_s_waitcnt(0);
;     unsigned nloc = b.st[0], nx = b.st[1];
;     if (nloc == 0u) { xcd_barrier_complete(bar, b.x, nloc, nx); b.st[0] = nloc; b.st[1] = nx; }
;     const unsigned old = xb_add(&bar[XB_XSUB(b.x)], 1u);
;     const unsigned gen = old / nloc;
;     if (old + 1u == (gen + 1u) * nloc) {
;       __builtin_amdgcn_fence(__ATOMIC_RELEASE, "agent");
;       asm volatile("s_waitcnt vmcnt(0)" ::: "memory");
;       const unsigned og = xb_add(&bar[XB_TOP], 1u);
;       const unsigned tg = og / nx;
;       if (og + 1u == (tg + 1u) * nx) xb_add(&bar[XB_TOPGEN], 1u);
;       else XB_SPIN(xb_ld(&bar[XB_TOPGEN]) == tg, bar);
;       __builtin_amdgcn_fence(__ATOMIC_ACQUIRE, "agent");
;       xb_add(&bar[XB_XGEN(b.x)], 1u);
;       asm volatile("s_waitcnt vmcnt(0)" ::: "memory");
;     } else {
;       XB_SPIN(xb_ld(&bar[XB_XGEN(b.x)]) == gen, bar);
;       __builtin_amdgcn_fence(__ATOMIC_ACQUIRE, "agent");
;       asm volatile("s_waitcnt vmcnt(0)" ::: "memory");
;     }
;   }
;   __syncthreads();
; }
.Lgb3_done:
.LBB0_475:
	s_or_b64 exec, exec, s[38:39]
	v_readlane_b32 s98, v240, 48
	s_add_i32 s98, s98, 1
	s_nop 0
	v_writelane_b32 v240, s98, 48
	v_mov_b32_e32 v7, v156
	s_waitcnt lgkmcnt(0)
	s_barrier
	v_readlane_b32 s38, v241, 2
	v_ashrrev_i32_e32 v8, 6, v7
	s_movk_i32 s12, 0x900
	v_add_u32_e32 v79, s38, v8
	v_and_b32_e32 v6, 63, v7
	v_cmp_gt_i32_e32 vcc, s12, v79
	v_and_b32_e32 v78, 31, v7
	v_lshlrev_b32_e32 v5, 5, v8
	s_and_saveexec_b64 s[52:53], vcc
	s_cbranch_execz .LBB0_480
	v_readlane_b32 s12, v241, 30
	v_lshlrev_b32_e32 v0, 2, v78
	v_readlane_b32 s14, v241, 32
	v_readlane_b32 s15, v241, 33
	v_readlane_b32 s12, v241, 25
	v_cmp_gt_u32_e32 vcc, 32, v6
	v_lshl_add_u64 v[2:3], s[14:15], 0, v[0:1]
	v_add_u32_e32 v0, -1, v157
	v_cmp_lt_i32_e64 s[38:39], v0, v170
	v_add3_u32 v4, s12, v5, v78
	s_lshl_b32 s56, s58, 5
	v_cndmask_b32_e64 v0, v0, v157, s[38:39]
	v_lshlrev_b32_e32 v9, 2, v0
	v_add_u32_e32 v0, -2, v157
	v_cmp_lt_i32_e64 s[40:41], v0, v170
	v_cmp_eq_u32_e64 s[38:39], 0, v78
	v_sub_u32_e32 v14, 0, v4
	v_cndmask_b32_e64 v0, v0, v157, s[40:41]
	v_lshlrev_b32_e32 v10, 2, v0
	v_add_u32_e32 v0, -4, v157
	v_cmp_lt_i32_e64 s[42:43], v0, v170
	v_cmp_gt_u32_e64 s[40:41], 2, v78
	s_mov_b64 s[54:55], 0
	v_cndmask_b32_e64 v0, v0, v157, s[42:43]
	v_lshlrev_b32_e32 v11, 2, v0
	v_add_u32_e32 v0, -8, v157
	v_cmp_lt_i32_e64 s[44:45], v0, v170
	v_cmp_gt_u32_e64 s[42:43], 4, v78
	v_mov_b32_e32 v15, v79
	v_cndmask_b32_e64 v0, v0, v157, s[44:45]
	v_lshlrev_b32_e32 v12, 2, v0
	v_add_u32_e32 v0, -16, v157
	v_cmp_lt_i32_e64 s[46:47], v0, v170
	v_cmp_gt_u32_e64 s[44:45], 8, v78
	v_readlane_b32 s13, v241, 31
	v_cndmask_b32_e64 v0, v0, v157, s[46:47]
	v_lshlrev_b32_e32 v13, 2, v0
	v_cmp_gt_u32_e64 s[46:47], 16, v78
	s_branch .LBB0_478

; __device__ __forceinline__ unsigned xb_ld(unsigned* p) { return __hip_atomic_load(p, __ATOMIC_RELAXED, __HIP_MEMORY_SCOPE_AGENT); }
; __device__ __forceinline__ unsigned xb_add(unsigned* p, unsigned v) { return __hip_atomic_fetch_add(p, v, __ATOMIC_RELAXED, __HIP_MEMORY_SCOPE_AGENT); }
; #define XB_SPIN(cond, bar) do { unsigned _sp = 0; while (cond) { __builtin_amdgcn_s_sleep(1); \
;     if ((++_sp & 255u) == 0u) { if (xb_ld(&(bar)[XB_TMO])) break; if (_sp > XB_SPIN_CAP) { atomicAdd(&(bar)[XB_TMO], 1u); break; } } } } while (0)
; __device__ void ph_scan(const Params& p, int l, int g, char* smem) {
;   const int b = blockIdx.x;
;   __shared__ int tb_s[2];
;   int u0, ustep;
;   if (gridDim.x == 512) {
;     ustep = 512;
;     u0 = b < 128 ? 128 + b : (b < 256 ? b - 128 : (b < 384 ? b : 384));
;   } else { u0 = b; ustep = gridDim.x; }
;   for (int u = u0; u < 384; u += ustep) scan_unit_mma(p, l, g, u, *(CSmem*)smem);
; __device__ __forceinline__ void xcd_barrier(const XcdBarrier& b) {
;   asm volatile("s_waitcnt vmcnt(0)" ::: "memory");
;   __syncthreads();
;   if (threadIdx.x == 0) {
;     unsigned* bar = b.bar;
;     __builtin_amdgcn_s_waitcnt(0);
;     unsigned nloc = b.st[0], nx = b.st[1];
;     if (nloc == 0u) { xcd_barrier_complete(bar, b.x, nloc, nx); b.st[0] = nloc; b.st[1] = nx; }
;     const unsigned old = xb_add(&bar[XB_XSUB(b.x)], 1u);
;     const unsigned gen = old / nloc;
;     if (old + 1u == (gen + 1u) * nloc) {
;       __builtin_amdgcn_fence(__ATOMIC_RELEASE, "agent");
;       asm volatile("s_waitcnt vmcnt(0)" ::: "memory");
;       const unsigned og = xb_add(&bar[XB_TOP], 1u);
;       const unsigned tg = og / nx;
;       if (og + 1u == (tg + 1u) * nx) xb_add(&bar[XB_TOPGEN], 1u);
;       else XB_SPIN(xb_ld(&bar[XB_TOPGEN]) == tg, bar);
;       __builtin_amdgcn_fence(__ATOMIC_ACQUIRE, "agent");
;       xb_add(&bar[XB_XGEN(b.x)], 1u);
;       asm volatile("s_waitcnt vmcnt(0)" ::: "memory");
;     } else {
;       XB_SPIN(xb_ld(&bar[XB_XGEN(b.x)]) == gen, bar);
;       __builtin_amdgcn_fence(__ATOMIC_ACQUIRE, "agent");
;       asm volatile("s_waitcnt vmcnt(0)" ::: "memory");
;     }
;   }
;   __syncthreads();
; }
.Lgb4_done:
.LBB0_609:
	s_or_b64 exec, exec, s[38:39]
	v_readlane_b32 s98, v240, 48
	s_add_i32 s98, s98, 1
	s_nop 0
	v_writelane_b32 v240, s98, 48
	v_readlane_b32 s12, v241, 23
	v_readlane_b32 s13, v241, 24
	s_andn2_b64 vcc, exec, s[12:13]
	v_readlane_b32 s70, v241, 22
	s_waitcnt lgkmcnt(0)
	s_barrier
	s_cbranch_vccz .LBB0_612

; __device__ __forceinline__ int otid() { int t = threadIdx.x; asm volatile("" : "+v"(t)); return t; }
; __device__ __forceinline__ unsigned xb_ld(unsigned* p) { return __hip_atomic_load(p, __ATOMIC_RELAXED, __HIP_MEMORY_SCOPE_AGENT); }
; __device__ __forceinline__ unsigned xb_add(unsigned* p, unsigned v) { return __hip_atomic_fetch_add(p, v, __ATOMIC_RELAXED, __HIP_MEMORY_SCOPE_AGENT); }
; #define XB_SPIN(cond, bar) do { unsigned _sp = 0; while (cond) { __builtin_amdgcn_s_sleep(1); \
;     if ((++_sp & 255u) == 0u) { if (xb_ld(&(bar)[XB_TMO])) break; if (_sp > XB_SPIN_CAP) { atomicAdd(&(bar)[XB_TMO], 1u); break; } } } } while (0)
; __device__ void ph_brfin(const Params& p, int l, int g) {
;   const int tid = otid();
;   const int lane = tid & 63;
;   const int gw = blockIdx.x * 4 + (tid >> 6), nw = gridDim.x * 4;
;   uint4 na0, na1, nb0, nb1, nz0, nz1, ng0, ng1;
;   float4 no0, no1, no2, no3;
;   const uint4 zz = uint4{0u, 0u, 0u, 0u};
;   na0 = na1 = nb0 = nb1 = nz0 = nz1 = ng0 = ng1 = zz;
;   no0 = no1 = no2 = no3 = float4{0.f, 0.f, 0.f, 0.f};
;     ...
;   BR_LOAD(gw)
; __device__ __forceinline__ void xcd_barrier(const XcdBarrier& b) {
;   asm volatile("s_waitcnt vmcnt(0)" ::: "memory");
;   __syncthreads();
;   if (threadIdx.x == 0) {
;     unsigned* bar = b.bar;
;     __builtin_amdgcn_s_waitcnt(0);
;     unsigned nloc = b.st[0], nx = b.st[1];
;     if (nloc == 0u) { xcd_barrier_complete(bar, b.x, nloc, nx); b.st[0] = nloc; b.st[1] = nx; }
;     const unsigned old = xb_add(&bar[XB_XSUB(b.x)], 1u);
;     const unsigned gen = old / nloc;
;     if (old + 1u == (gen + 1u) * nloc) {
;       __builtin_amdgcn_fence(__ATOMIC_RELEASE, "agent");
;       asm volatile("s_waitcnt vmcnt(0)" ::: "memory");
;       const unsigned og = xb_add(&bar[XB_TOP], 1u);
;       const unsigned tg = og / nx;
;       if (og + 1u == (tg + 1u) * nx) xb_add(&bar[XB_TOPGEN], 1u);
;       else XB_SPIN(xb_ld(&bar[XB_TOPGEN]) == tg, bar);
;       __builtin_amdgcn_fence(__ATOMIC_ACQUIRE, "agent");
;       xb_add(&bar[XB_XGEN(b.x)], 1u);
;       asm volatile("s_waitcnt vmcnt(0)" ::: "memory");
;     } else {
;       XB_SPIN(xb_ld(&bar[XB_XGEN(b.x)]) == gen, bar);
;       __builtin_amdgcn_fence(__ATOMIC_ACQUIRE, "agent");
;       asm volatile("s_waitcnt vmcnt(0)" ::: "memory");
;     }
;   }
;   __syncthreads();
; }
.Lgb5_done:
.LBB0_899:
	s_or_b64 exec, exec, s[38:39]
	v_readlane_b32 s98, v240, 48
	s_add_i32 s98, s98, 1
	s_nop 0
	v_writelane_b32 v240, s98, 48
	v_mov_b32_e32 v0, v156
	s_waitcnt lgkmcnt(0)
	s_barrier
	v_readlane_b32 s38, v241, 2
	v_ashrrev_i32_e32 v16, 6, v0
	s_movk_i32 s12, 0x6c00
	v_add_u32_e32 v108, s38, v16
	v_cmp_gt_i32_e32 vcc, s12, v108
	s_and_saveexec_b64 s[44:45], vcc
	s_cbranch_execz .LBB0_920
	v_and_b32_e32 v17, 63, v0
	v_mul_hi_i32 v0, v108, s59
	v_lshrrev_b32_e32 v2, 31, v0
	v_ashrrev_i32_e32 v0, 11, v0
	v_add_u32_e32 v18, v0, v2
	v_mul_i32_i24_e32 v0, 0x2400, v18
	v_sub_u32_e32 v14, v108, v0
	v_mul_i32_i24_e32 v0, 0xe39, v14
	v_lshrrev_b32_e32 v2, 31, v0
	v_lshrrev_b32_e32 v0, 23, v0
	v_add_u16_e32 v0, v0, v2
	v_mul_lo_u16_e32 v0, 0x900, v0
	v_readlane_b32 s12, v240, 2
	v_sub_u16_e32 v0, v14, v0
	v_readlane_b32 s13, v240, 3
	v_cmp_lt_i16_e32 vcc, s24, v0
	s_xor_b64 s[46:47], s[12:13], -1
	s_or_b64 s[38:39], s[46:47], vcc
	v_lshlrev_b32_e32 v0, 4, v17
	s_and_saveexec_b64 s[40:41], s[38:39]
	s_xor_b64 s[42:43], exec, s[40:41]
	s_cbranch_execz .LBB0_904
	v_mov_b64_e32 v[2:3], s[88:89]
	v_lshlrev_b32_e32 v4, 10, v18
	v_mad_i64_i32 v[2:3], s[38:39], v14, s26, v[2:3]
	v_ashrrev_i32_e32 v5, 31, v4
	v_lshl_add_u64 v[2:3], v[4:5], 1, v[2:3]
	v_lshlrev_b32_e32 v4, 5, v17
	v_mov_b32_e32 v5, v1
	v_lshl_add_u64 v[2:3], v[2:3], 0, v[4:5]
	s_mov_b64 s[12:13], 0x3600000
	v_lshl_add_u64 v[6:7], v[2:3], 0, s[12:13]
	global_load_dwordx4 v[82:85], v[2:3], off offset:16
	global_load_dwordx4 v[90:93], v[2:3], off
	v_add_co_u32_e32 v2, vcc, 0x3600000, v2
	s_movk_i32 s12, 0x2400
	s_nop 0
	v_addc_co_u32_e32 v3, vcc, 0, v3, vcc
	global_load_dwordx4 v[94:97], v[2:3], off
	global_load_dwordx4 v[86:89], v[6:7], off offset:16
	v_add_u32_e32 v2, 0xffffdc00, v108
	v_ashrrev_i32_e32 v15, 31, v14
	v_add_u32_e32 v6, 0x23ff, v108
	v_cmp_gt_u32_e64 s[38:39], s12, v2
	s_movk_i32 s10, 0x47ff
	v_lshlrev_b64 v[2:3], 15, v[14:15]
	v_cndmask_b32_e64 v7, v181, v182, s[38:39]
	v_cmp_gt_u32_e64 s[40:41], s10, v6
	v_lshl_add_u64 v[14:15], s[86:87], 0, v[2:3]
	v_mov_b32_e32 v3, v1
	v_cndmask_b32_e64 v2, v7, v183, s[40:41]
	v_lshlrev_b32_e32 v2, 1, v2
	v_lshl_add_u64 v[2:3], v[14:15], 0, v[2:3]
	v_lshl_add_u64 v[2:3], v[2:3], 0, v[4:5]
	global_load_dwordx4 v[10:13], v[2:3], off offset:16
	global_load_dwordx4 v[70:73], v[2:3], off
	v_mov_b32_e32 v4, v1
	v_mov_b32_e32 v2, v1
	v_mov_b32_e32 v3, v1
	v_mov_b64_e32 v[8:9], v[4:5]
	v_cmp_lt_i32_e32 vcc, s10, v108
	v_mov_b64_e32 v[6:7], v[2:3]
	s_and_saveexec_b64 s[48:49], vcc
	s_cbranch_execz .LBB0_903
	v_lshlrev_b32_e32 v2, 1, v0
	v_mov_b32_e32 v3, v1
	v_lshl_add_u64 v[2:3], v[14:15], 0, v[2:3]
	s_mov_b64 s[12:13], 0x5800
	v_lshl_add_u64 v[4:5], v[2:3], 0, s[12:13]
	v_add_co_u32_e32 v2, vcc, 0x5000, v2
	s_nop 1
	v_addc_co_u32_e32 v3, vcc, 0, v3, vcc
	global_load_dwordx4 v[6:9], v[2:3], off offset:2048
	s_nop 0
	global_load_dwordx4 v[2:5], v[4:5], off offset:16

; __device__ __forceinline__ unsigned xb_ld(unsigned* p) { return __hip_atomic_load(p, __ATOMIC_RELAXED, __HIP_MEMORY_SCOPE_AGENT); }
; __device__ __forceinline__ unsigned xb_add(unsigned* p, unsigned v) { return __hip_atomic_fetch_add(p, v, __ATOMIC_RELAXED, __HIP_MEMORY_SCOPE_AGENT); }
; #define XB_SPIN(cond, bar) do { unsigned _sp = 0; while (cond) { __builtin_amdgcn_s_sleep(1); \
;     if ((++_sp & 255u) == 0u) { if (xb_ld(&(bar)[XB_TMO])) break; if (_sp > XB_SPIN_CAP) { atomicAdd(&(bar)[XB_TMO], 1u); break; } } } } while (0)
; __device__ __forceinline__ void xcd_barrier(const XcdBarrier& b) {
;   asm volatile("s_waitcnt vmcnt(0)" ::: "memory");
;   __syncthreads();
;   if (threadIdx.x == 0) {
;     unsigned* bar = b.bar;
;     __builtin_amdgcn_s_waitcnt(0);
;     unsigned nloc = b.st[0], nx = b.st[1];
;     if (nloc == 0u) { xcd_barrier_complete(bar, b.x, nloc, nx); b.st[0] = nloc; b.st[1] = nx; }
;     const unsigned old = xb_add(&bar[XB_XSUB(b.x)], 1u);
;     const unsigned gen = old / nloc;
;     if (old + 1u == (gen + 1u) * nloc) {
;       __builtin_amdgcn_fence(__ATOMIC_RELEASE, "agent");
;       asm volatile("s_waitcnt vmcnt(0)" ::: "memory");
;       const unsigned og = xb_add(&bar[XB_TOP], 1u);
;       const unsigned tg = og / nx;
;       if (og + 1u == (tg + 1u) * nx) xb_add(&bar[XB_TOPGEN], 1u);
;       else XB_SPIN(xb_ld(&bar[XB_TOPGEN]) == tg, bar);
;       __builtin_amdgcn_fence(__ATOMIC_ACQUIRE, "agent");
;       xb_add(&bar[XB_XGEN(b.x)], 1u);
;       asm volatile("s_waitcnt vmcnt(0)" ::: "memory");
;     } else {
;       XB_SPIN(xb_ld(&bar[XB_XGEN(b.x)]) == gen, bar);
;       __builtin_amdgcn_fence(__ATOMIC_ACQUIRE, "agent");
;       asm volatile("s_waitcnt vmcnt(0)" ::: "memory");
;     }
;   }
;   __syncthreads();
; }
.LBB0_956:
	s_waitcnt lgkmcnt(0)
	v_readlane_b32 s42, v242, 58
	v_readlane_b32 s43, v242, 59
	v_mov_b32_e32 v4, 1
	v_readlane_b32 s46, v240, 48
	s_add_i32 s46, s46, 1
	v_mul_lo_u32 v6, v3, s46
	v_mul_lo_u32 v5, v2, s46
	s_nop 1
	global_atomic_add v4, v1, v4, s[42:43] sc0
	buffer_inv sc1
	v_readlane_b32 s44, v242, 62
	v_readlane_b32 s45, v242, 63
	s_waitcnt vmcnt(1)
	v_add_u32_e32 v4, 1, v4
	v_cmp_eq_u32_e32 vcc, v4, v6
	s_cbranch_vccz .Lgb6_poll
	buffer_wbl2 sc1
	s_waitcnt vmcnt(0) lgkmcnt(0)
	v_mov_b32_e32 v4, 1
	global_atomic_add v1, v4, s[44:45]

; __device__ __forceinline__ unsigned xb_ld(unsigned* p) { return __hip_atomic_load(p, __ATOMIC_RELAXED, __HIP_MEMORY_SCOPE_AGENT); }
; __device__ __forceinline__ unsigned xb_add(unsigned* p, unsigned v) { return __hip_atomic_fetch_add(p, v, __ATOMIC_RELAXED, __HIP_MEMORY_SCOPE_AGENT); }
; #define XB_SPIN(cond, bar) do { unsigned _sp = 0; while (cond) { __builtin_amdgcn_s_sleep(1); \
;     if ((++_sp & 255u) == 0u) { if (xb_ld(&(bar)[XB_TMO])) break; if (_sp > XB_SPIN_CAP) { atomicAdd(&(bar)[XB_TMO], 1u); break; } } } } while (0)
; __device__ void ph_gemm_merge(const Params& p, int l, char* smem) {
;   for (int t = blockIdx.x; t < 72 * 8; t += gridDim.x) {
;     int nt = t / 72, mt = t % 72;
;     if (l == 1 && (mt % 18) < 2) continue;
; __device__ __forceinline__ void xcd_barrier(const XcdBarrier& b) {
;   asm volatile("s_waitcnt vmcnt(0)" ::: "memory");
;   __syncthreads();
;   if (threadIdx.x == 0) {
;     unsigned* bar = b.bar;
;     __builtin_amdgcn_s_waitcnt(0);
;     unsigned nloc = b.st[0], nx = b.st[1];
;     if (nloc == 0u) { xcd_barrier_complete(bar, b.x, nloc, nx); b.st[0] = nloc; b.st[1] = nx; }
;     const unsigned old = xb_add(&bar[XB_XSUB(b.x)], 1u);
;     const unsigned gen = old / nloc;
;     if (old + 1u == (gen + 1u) * nloc) {
;       __builtin_amdgcn_fence(__ATOMIC_RELEASE, "agent");
;       asm volatile("s_waitcnt vmcnt(0)" ::: "memory");
;       const unsigned og = xb_add(&bar[XB_TOP], 1u);
;       const unsigned tg = og / nx;
;       if (og + 1u == (tg + 1u) * nx) xb_add(&bar[XB_TOPGEN], 1u);
;       else XB_SPIN(xb_ld(&bar[XB_TOPGEN]) == tg, bar);
;       __builtin_amdgcn_fence(__ATOMIC_ACQUIRE, "agent");
;       xb_add(&bar[XB_XGEN(b.x)], 1u);
;       asm volatile("s_waitcnt vmcnt(0)" ::: "memory");
;     } else {
;       XB_SPIN(xb_ld(&bar[XB_XGEN(b.x)]) == gen, bar);
;       __builtin_amdgcn_fence(__ATOMIC_ACQUIRE, "agent");
;       asm volatile("s_waitcnt vmcnt(0)" ::: "memory");
;     }
;   }
;   __syncthreads();
; }
.Lgb6_done:
.LBB0_992:
	s_or_b64 exec, exec, s[40:41]
	v_readlane_b32 s98, v240, 48
	s_add_i32 s98, s98, 1
	s_nop 0
	v_writelane_b32 v240, s98, 48
	v_readlane_b32 s12, v241, 15
	v_readlane_b32 s13, v241, 16
	s_andn2_b64 vcc, exec, s[12:13]
	s_waitcnt lgkmcnt(0)
	s_barrier
	s_cbranch_vccnz .LBB0_1001
	v_readlane_b32 s65, v242, 2
	s_branch .LBB0_995

; __device__ __forceinline__ unsigned xb_ld(unsigned* p) { return __hip_atomic_load(p, __ATOMIC_RELAXED, __HIP_MEMORY_SCOPE_AGENT); }
; __device__ __forceinline__ unsigned xb_add(unsigned* p, unsigned v) { return __hip_atomic_fetch_add(p, v, __ATOMIC_RELAXED, __HIP_MEMORY_SCOPE_AGENT); }
; #define XB_SPIN(cond, bar) do { unsigned _sp = 0; while (cond) { __builtin_amdgcn_s_sleep(1); \
;     if ((++_sp & 255u) == 0u) { if (xb_ld(&(bar)[XB_TMO])) break; if (_sp > XB_SPIN_CAP) { atomicAdd(&(bar)[XB_TMO], 1u); break; } } } } while (0)
; __device__ void ph_gemm_out(const Params& p, int l, int g, char* smem) {
;   for (int t = (int)gridDim.x - 1 - (int)blockIdx.x; t < 72 * 8; t += gridDim.x) {
;     int nt = t / 72, mt = t % 72;
;     if (l == 1 && (mt % 18) < 2) continue;
; __device__ __forceinline__ void xcd_barrier(const XcdBarrier& b) {
;   asm volatile("s_waitcnt vmcnt(0)" ::: "memory");
;   __syncthreads();
;   if (threadIdx.x == 0) {
;     unsigned* bar = b.bar;
;     __builtin_amdgcn_s_waitcnt(0);
;     unsigned nloc = b.st[0], nx = b.st[1];
;     if (nloc == 0u) { xcd_barrier_complete(bar, b.x, nloc, nx); b.st[0] = nloc; b.st[1] = nx; }
;     const unsigned old = xb_add(&bar[XB_XSUB(b.x)], 1u);
;     const unsigned gen = old / nloc;
;     if (old + 1u == (gen + 1u) * nloc) {
;       __builtin_amdgcn_fence(__ATOMIC_RELEASE, "agent");
;       asm volatile("s_waitcnt vmcnt(0)" ::: "memory");
;       const unsigned og = xb_add(&bar[XB_TOP], 1u);
;       const unsigned tg = og / nx;
;       if (og + 1u == (tg + 1u) * nx) xb_add(&bar[XB_TOPGEN], 1u);
;       else XB_SPIN(xb_ld(&bar[XB_TOPGEN]) == tg, bar);
;       __builtin_amdgcn_fence(__ATOMIC_ACQUIRE, "agent");
;       xb_add(&bar[XB_XGEN(b.x)], 1u);
;       asm volatile("s_waitcnt vmcnt(0)" ::: "memory");
;     } else {
;       XB_SPIN(xb_ld(&bar[XB_XGEN(b.x)]) == gen, bar);
;       __builtin_amdgcn_fence(__ATOMIC_ACQUIRE, "agent");
;       asm volatile("s_waitcnt vmcnt(0)" ::: "memory");
;     }
;   }
;   __syncthreads();
; }
.Lgb7_done:
.LBB0_1053:
	s_or_b64 exec, exec, s[40:41]
	v_readlane_b32 s98, v240, 48
	s_add_i32 s98, s98, 1
	s_nop 0
	v_writelane_b32 v240, s98, 48
	v_readlane_b32 s12, v241, 20
	v_readlane_b32 s13, v241, 21
	s_andn2_b64 vcc, exec, s[12:13]
	s_waitcnt lgkmcnt(0)
	s_barrier
	s_cbranch_vccnz .LBB0_1076
	v_readlane_b32 s10, v240, 45
	s_lshl_b32 s44, s10, 2
	v_readlane_b32 s45, v241, 19
	s_branch .LBB0_1057

; __device__ __forceinline__ unsigned xb_ld(unsigned* p) { return __hip_atomic_load(p, __ATOMIC_RELAXED, __HIP_MEMORY_SCOPE_AGENT); }
; __device__ __forceinline__ unsigned xb_add(unsigned* p, unsigned v) { return __hip_atomic_fetch_add(p, v, __ATOMIC_RELAXED, __HIP_MEMORY_SCOPE_AGENT); }
; #define XB_SPIN(cond, bar) do { unsigned _sp = 0; while (cond) { __builtin_amdgcn_s_sleep(1); \
;     if ((++_sp & 255u) == 0u) { if (xb_ld(&(bar)[XB_TMO])) break; if (_sp > XB_SPIN_CAP) { atomicAdd(&(bar)[XB_TMO], 1u); break; } } } } while (0)
; __device__ __forceinline__ void xcd_barrier(const XcdBarrier& b) {
;   asm volatile("s_waitcnt vmcnt(0)" ::: "memory");
;   __syncthreads();
;   if (threadIdx.x == 0) {
;     unsigned* bar = b.bar;
;     __builtin_amdgcn_s_waitcnt(0);
;     unsigned nloc = b.st[0], nx = b.st[1];
;     if (nloc == 0u) { xcd_barrier_complete(bar, b.x, nloc, nx); b.st[0] = nloc; b.st[1] = nx; }
;     const unsigned old = xb_add(&bar[XB_XSUB(b.x)], 1u);
;     const unsigned gen = old / nloc;
;     if (old + 1u == (gen + 1u) * nloc) {
;       __builtin_amdgcn_fence(__ATOMIC_RELEASE, "agent");
;       asm volatile("s_waitcnt vmcnt(0)" ::: "memory");
;       const unsigned og = xb_add(&bar[XB_TOP], 1u);
;       const unsigned tg = og / nx;
;       if (og + 1u == (tg + 1u) * nx) xb_add(&bar[XB_TOPGEN], 1u);
;       else XB_SPIN(xb_ld(&bar[XB_TOPGEN]) == tg, bar);
;       __builtin_amdgcn_fence(__ATOMIC_ACQUIRE, "agent");
;       xb_add(&bar[XB_XGEN(b.x)], 1u);
;       asm volatile("s_waitcnt vmcnt(0)" ::: "memory");
;     } else {
;       XB_SPIN(xb_ld(&bar[XB_XGEN(b.x)]) == gen, bar);
;       __builtin_amdgcn_fence(__ATOMIC_ACQUIRE, "agent");
;       asm volatile("s_waitcnt vmcnt(0)" ::: "memory");
;     }
;   }
;   __syncthreads();
; }
.LBB0_1180:
	s_waitcnt lgkmcnt(0)
	v_readlane_b32 s40, v242, 58
	v_readlane_b32 s41, v242, 59
	v_mov_b32_e32 v4, 1
	v_readlane_b32 s46, v240, 48
	s_add_i32 s46, s46, 1
	v_mul_lo_u32 v6, v3, s46
	v_mul_lo_u32 v5, v2, s46
	s_nop 1
	global_atomic_add v4, v1, v4, s[40:41] sc0
	buffer_inv sc1
	v_readlane_b32 s44, v242, 62
	v_readlane_b32 s45, v242, 63
	s_waitcnt vmcnt(1)
	v_add_u32_e32 v4, 1, v4
	v_cmp_eq_u32_e32 vcc, v4, v6
	s_cbranch_vccz .Lgb8_poll
	buffer_wbl2 sc1
	s_waitcnt vmcnt(0) lgkmcnt(0)
	v_mov_b32_e32 v4, 1
	global_atomic_add v1, v4, s[44:45]

; __device__ __forceinline__ unsigned xb_ld(unsigned* p) { return __hip_atomic_load(p, __ATOMIC_RELAXED, __HIP_MEMORY_SCOPE_AGENT); }
; __device__ __forceinline__ unsigned xb_add(unsigned* p, unsigned v) { return __hip_atomic_fetch_add(p, v, __ATOMIC_RELAXED, __HIP_MEMORY_SCOPE_AGENT); }
; #define XB_SPIN(cond, bar) do { unsigned _sp = 0; while (cond) { __builtin_amdgcn_s_sleep(1); \
;     if ((++_sp & 255u) == 0u) { if (xb_ld(&(bar)[XB_TMO])) break; if (_sp > XB_SPIN_CAP) { atomicAdd(&(bar)[XB_TMO], 1u); break; } } } } while (0)
; __device__ __forceinline__ void xcd_barrier(const XcdBarrier& b) {
;   asm volatile("s_waitcnt vmcnt(0)" ::: "memory");
;   __syncthreads();
;   if (threadIdx.x == 0) {
;     unsigned* bar = b.bar;
;     __builtin_amdgcn_s_waitcnt(0);
;     unsigned nloc = b.st[0], nx = b.st[1];
;     if (nloc == 0u) { xcd_barrier_complete(bar, b.x, nloc, nx); b.st[0] = nloc; b.st[1] = nx; }
;     const unsigned old = xb_add(&bar[XB_XSUB(b.x)], 1u);
;     const unsigned gen = old / nloc;
;     if (old + 1u == (gen + 1u) * nloc) {
;       __builtin_amdgcn_fence(__ATOMIC_RELEASE, "agent");
;       asm volatile("s_waitcnt vmcnt(0)" ::: "memory");
;       const unsigned og = xb_add(&bar[XB_TOP], 1u);
;       const unsigned tg = og / nx;
;       if (og + 1u == (tg + 1u) * nx) xb_add(&bar[XB_TOPGEN], 1u);
;       else XB_SPIN(xb_ld(&bar[XB_TOPGEN]) == tg, bar);
;       __builtin_amdgcn_fence(__ATOMIC_ACQUIRE, "agent");
;       xb_add(&bar[XB_XGEN(b.x)], 1u);
;       asm volatile("s_waitcnt vmcnt(0)" ::: "memory");
;     } else {
;       XB_SPIN(xb_ld(&bar[XB_XGEN(b.x)]) == gen, bar);
;       __builtin_amdgcn_fence(__ATOMIC_ACQUIRE, "agent");
;       asm volatile("s_waitcnt vmcnt(0)" ::: "memory");
;     }
;   }
;   __syncthreads();
; }
.Lgb8_done:
	s_mov_b64 s[42:43], 0
	s_getpc_b64 s[98:99]
